# strategy 7 (instruction selection): mLSTM reduction as DPP reduce-scatter (5 adds) + bf16 short stores from lanes 0/8, next-token LDS reads as wait-state fillers
# baseline (speedup 1.0000x reference)
.Lml2_nsc1:
	v_add_u32_e32 v64, s20, v69
	v_add_u32_e32 v65, s20, v70
	v_add_u32_e32 v66, s20, v71
	v_add_u32_e32 v67, s20, v72
	v_add_u32_e32 v68, s20, v73
	v_add_u32_e32 v58, s18, v2
	v_add_u32_e32 v59, s18, v3
	v_mov_b32_e32 v60, s18
	v_add_u32_e32 v61, s19, v2
	v_add_u32_e32 v62, s19, v3
	v_mov_b32_e32 v63, s19
	v_mov_b32_e32 v6, 0
	v_mov_b32_e32 v7, 0
	v_mov_b32_e32 v8, 0
	v_mov_b32_e32 v9, 0
	v_mov_b32_e32 v10, 0
	v_mov_b32_e32 v11, 0
	v_mov_b32_e32 v12, 0
	v_mov_b32_e32 v13, 0
	v_mov_b32_e32 v14, 0
	v_mov_b32_e32 v15, 0
	v_mov_b32_e32 v16, 0
	v_mov_b32_e32 v17, 0
	s_mov_b32 s16, 0
	s_waitcnt vmcnt(0) lgkmcnt(0)
	s_barrier
	s_mov_b32 s18, 0x01010101
	s_mov_b32 s19, 0x01010101
	v_and_b32_e32 v58, 8, v198
	v_lshrrev_b32_e32 v58, 2, v58
	v_add_u32_e32 v58, v4, v58
	ds_read_b128 v[40:43], v1 offset:14848
	ds_read_b128 v[30:33], v2 offset:8448
	ds_read_b64 v[38:39], v3 offset:12544
	ds_read_b128 v[34:37], v2 offset:8704

.Lml2_back0_0:
	v_cvt_pk_bf16_f32 v28, v26, v26
	s_mov_b64 exec, s[18:19]
	global_store_short v58, v28, s[14:15] offset:-4096
	s_mov_b64 exec, -1
	s_waitcnt lgkmcnt(2)
	v_pk_mul_f32 v[18:19], v[44:45], v[54:55] op_sel:[0,1] op_sel_hi:[1,1]
	v_pk_mul_f32 v[20:21], v[46:47], v[54:55] op_sel:[0,1] op_sel_hi:[1,1]
	s_waitcnt lgkmcnt(1)
	v_pk_mul_f32 v[22:23], v[52:53], v[18:19] op_sel:[0,0] op_sel_hi:[1,0]
	v_pk_fma_f32 v[6:7], v[6:7], v[54:55], v[22:23] op_sel_hi:[1,0,1]
	s_waitcnt lgkmcnt(0)
	v_pk_mul_f32 v[26:27], v[6:7], v[48:49] op_sel_hi:[1,0]
	v_pk_mul_f32 v[24:25], v[52:53], v[18:19] op_sel:[0,1] op_sel_hi:[1,1]
	v_pk_fma_f32 v[8:9], v[8:9], v[54:55], v[24:25] op_sel_hi:[1,0,1]
	v_pk_fma_f32 v[26:27], v[8:9], v[48:49], v[26:27] op_sel:[0,1,0] op_sel_hi:[1,1,1]
	v_pk_mul_f32 v[22:23], v[52:53], v[20:21] op_sel:[0,0] op_sel_hi:[1,0]
	v_pk_fma_f32 v[10:11], v[10:11], v[54:55], v[22:23] op_sel_hi:[1,0,1]
	v_pk_fma_f32 v[26:27], v[10:11], v[50:51], v[26:27] op_sel:[0,0,0] op_sel_hi:[1,0,1]
	v_pk_mul_f32 v[24:25], v[52:53], v[20:21] op_sel:[0,1] op_sel_hi:[1,1]
	v_pk_fma_f32 v[12:13], v[12:13], v[54:55], v[24:25] op_sel_hi:[1,0,1]
	v_pk_fma_f32 v[26:27], v[12:13], v[50:51], v[26:27] op_sel:[0,1,0] op_sel_hi:[1,1,1]
	v_pk_fma_f32 v[14:15], v[14:15], v[54:55], v[18:19] op_sel_hi:[1,0,1]
	v_pk_fma_f32 v[16:17], v[16:17], v[54:55], v[20:21] op_sel_hi:[1,0,1]
	v_add_f32_dpp v26, v26, v26 row_ror:8 row_mask:0xf bank_mask:0x3 bound_ctrl:1
	v_add_f32_dpp v26, v27, v27 row_ror:8 row_mask:0xf bank_mask:0xc bound_ctrl:1
	ds_read_b128 v[40:43], v1 offset:14880
	ds_read_b128 v[30:33], v2 offset:9472
	v_add_f32_dpp v26, v26, v26 row_half_mirror row_mask:0xf bank_mask:0xf bound_ctrl:1
	ds_read_b64 v[38:39], v3 offset:13056
	ds_read_b128 v[34:37], v2 offset:9728
	v_add_f32_dpp v26, v26, v26 quad_perm:[1,0,3,2] row_mask:0xf bank_mask:0xf bound_ctrl:1
	s_add_u32 s14, s14, 0x1000
	s_addc_u32 s15, s15, 0
	v_add_f32_dpp v26, v26, v26 quad_perm:[2,3,0,1] row_mask:0xf bank_mask:0xf bound_ctrl:1
	s_cmp_eq_u32 s21, 1
	s_cbranch_scc1 .Lml2_den0_1
.Lml2_back0_1:
	v_cvt_pk_bf16_f32 v28, v26, v26
	s_mov_b64 exec, s[18:19]
	global_store_short v58, v28, s[14:15] offset:-4096
	s_mov_b64 exec, -1
	s_waitcnt lgkmcnt(2)
	v_pk_mul_f32 v[18:19], v[30:31], v[40:41] op_sel:[0,1] op_sel_hi:[1,1]
	v_pk_mul_f32 v[20:21], v[32:33], v[40:41] op_sel:[0,1] op_sel_hi:[1,1]
	s_waitcnt lgkmcnt(1)
	v_pk_mul_f32 v[22:23], v[38:39], v[18:19] op_sel:[0,0] op_sel_hi:[1,0]
	v_pk_fma_f32 v[6:7], v[6:7], v[40:41], v[22:23] op_sel_hi:[1,0,1]
	s_waitcnt lgkmcnt(0)
	v_pk_mul_f32 v[26:27], v[6:7], v[34:35] op_sel_hi:[1,0]
	v_pk_mul_f32 v[24:25], v[38:39], v[18:19] op_sel:[0,1] op_sel_hi:[1,1]
	v_pk_fma_f32 v[8:9], v[8:9], v[40:41], v[24:25] op_sel_hi:[1,0,1]
	v_pk_fma_f32 v[26:27], v[8:9], v[34:35], v[26:27] op_sel:[0,1,0] op_sel_hi:[1,1,1]
	v_pk_mul_f32 v[22:23], v[38:39], v[20:21] op_sel:[0,0] op_sel_hi:[1,0]
	v_pk_fma_f32 v[10:11], v[10:11], v[40:41], v[22:23] op_sel_hi:[1,0,1]
	v_pk_fma_f32 v[26:27], v[10:11], v[36:37], v[26:27] op_sel:[0,0,0] op_sel_hi:[1,0,1]
	v_pk_mul_f32 v[24:25], v[38:39], v[20:21] op_sel:[0,1] op_sel_hi:[1,1]
	v_pk_fma_f32 v[12:13], v[12:13], v[40:41], v[24:25] op_sel_hi:[1,0,1]
	v_pk_fma_f32 v[26:27], v[12:13], v[36:37], v[26:27] op_sel:[0,1,0] op_sel_hi:[1,1,1]
	v_pk_fma_f32 v[14:15], v[14:15], v[40:41], v[18:19] op_sel_hi:[1,0,1]
	v_pk_fma_f32 v[16:17], v[16:17], v[40:41], v[20:21] op_sel_hi:[1,0,1]
	v_add_f32_dpp v26, v26, v26 row_ror:8 row_mask:0xf bank_mask:0x3 bound_ctrl:1
	v_add_f32_dpp v26, v27, v27 row_ror:8 row_mask:0xf bank_mask:0xc bound_ctrl:1
	ds_read_b128 v[54:57], v1 offset:14896
	ds_read_b128 v[44:47], v2 offset:9984
	v_add_f32_dpp v26, v26, v26 row_half_mirror row_mask:0xf bank_mask:0xf bound_ctrl:1
	ds_read_b64 v[52:53], v3 offset:13312
	ds_read_b128 v[48:51], v2 offset:10240
	v_add_f32_dpp v26, v26, v26 quad_perm:[1,0,3,2] row_mask:0xf bank_mask:0xf bound_ctrl:1
	s_add_u32 s14, s14, 0x1000
	s_addc_u32 s15, s15, 0
	v_add_f32_dpp v26, v26, v26 quad_perm:[2,3,0,1] row_mask:0xf bank_mask:0xf bound_ctrl:1
	s_cmp_eq_u32 s21, 2
	s_cbranch_scc1 .Lml2_den0_2
.Lml2_back0_2:
	v_cvt_pk_bf16_f32 v28, v26, v26
	s_mov_b64 exec, s[18:19]
	global_store_short v58, v28, s[14:15] offset:-4096
	s_mov_b64 exec, -1
	s_waitcnt lgkmcnt(2)
	v_pk_mul_f32 v[18:19], v[44:45], v[54:55] op_sel:[0,1] op_sel_hi:[1,1]
	v_pk_mul_f32 v[20:21], v[46:47], v[54:55] op_sel:[0,1] op_sel_hi:[1,1]
	s_waitcnt lgkmcnt(1)
	v_pk_mul_f32 v[22:23], v[52:53], v[18:19] op_sel:[0,0] op_sel_hi:[1,0]
	v_pk_fma_f32 v[6:7], v[6:7], v[54:55], v[22:23] op_sel_hi:[1,0,1]
	s_waitcnt lgkmcnt(0)
	v_pk_mul_f32 v[26:27], v[6:7], v[48:49] op_sel_hi:[1,0]
	v_pk_mul_f32 v[24:25], v[52:53], v[18:19] op_sel:[0,1] op_sel_hi:[1,1]
	v_pk_fma_f32 v[8:9], v[8:9], v[54:55], v[24:25] op_sel_hi:[1,0,1]
	v_pk_fma_f32 v[26:27], v[8:9], v[48:49], v[26:27] op_sel:[0,1,0] op_sel_hi:[1,1,1]
	v_pk_mul_f32 v[22:23], v[52:53], v[20:21] op_sel:[0,0] op_sel_hi:[1,0]
	v_pk_fma_f32 v[10:11], v[10:11], v[54:55], v[22:23] op_sel_hi:[1,0,1]
	v_pk_fma_f32 v[26:27], v[10:11], v[50:51], v[26:27] op_sel:[0,0,0] op_sel_hi:[1,0,1]
	v_pk_mul_f32 v[24:25], v[52:53], v[20:21] op_sel:[0,1] op_sel_hi:[1,1]
	v_pk_fma_f32 v[12:13], v[12:13], v[54:55], v[24:25] op_sel_hi:[1,0,1]
	v_pk_fma_f32 v[26:27], v[12:13], v[50:51], v[26:27] op_sel:[0,1,0] op_sel_hi:[1,1,1]
	v_pk_fma_f32 v[14:15], v[14:15], v[54:55], v[18:19] op_sel_hi:[1,0,1]
	v_pk_fma_f32 v[16:17], v[16:17], v[54:55], v[20:21] op_sel_hi:[1,0,1]
	v_add_f32_dpp v26, v26, v26 row_ror:8 row_mask:0xf bank_mask:0x3 bound_ctrl:1
	v_add_f32_dpp v26, v27, v27 row_ror:8 row_mask:0xf bank_mask:0xc bound_ctrl:1
	ds_read_b128 v[40:43], v1 offset:14912
	ds_read_b128 v[30:33], v2 offset:10496
	v_add_f32_dpp v26, v26, v26 row_half_mirror row_mask:0xf bank_mask:0xf bound_ctrl:1
	ds_read_b64 v[38:39], v3 offset:13568
	ds_read_b128 v[34:37], v2 offset:10752
	v_add_f32_dpp v26, v26, v26 quad_perm:[1,0,3,2] row_mask:0xf bank_mask:0xf bound_ctrl:1
	s_add_u32 s14, s14, 0x1000
	s_addc_u32 s15, s15, 0
	v_add_f32_dpp v26, v26, v26 quad_perm:[2,3,0,1] row_mask:0xf bank_mask:0xf bound_ctrl:1
	s_cmp_eq_u32 s21, 3
	s_cbranch_scc1 .Lml2_den0_3
.Lml2_back0_3:
	v_cvt_pk_bf16_f32 v28, v26, v26
	s_mov_b64 exec, s[18:19]
	global_store_short v58, v28, s[14:15] offset:-4096
	s_mov_b64 exec, -1
	s_waitcnt lgkmcnt(2)
	v_pk_mul_f32 v[18:19], v[30:31], v[40:41] op_sel:[0,1] op_sel_hi:[1,1]
	v_pk_mul_f32 v[20:21], v[32:33], v[40:41] op_sel:[0,1] op_sel_hi:[1,1]
	s_waitcnt lgkmcnt(1)
	v_pk_mul_f32 v[22:23], v[38:39], v[18:19] op_sel:[0,0] op_sel_hi:[1,0]
	v_pk_fma_f32 v[6:7], v[6:7], v[40:41], v[22:23] op_sel_hi:[1,0,1]
	s_waitcnt lgkmcnt(0)
	v_pk_mul_f32 v[26:27], v[6:7], v[34:35] op_sel_hi:[1,0]
	v_pk_mul_f32 v[24:25], v[38:39], v[18:19] op_sel:[0,1] op_sel_hi:[1,1]
	v_pk_fma_f32 v[8:9], v[8:9], v[40:41], v[24:25] op_sel_hi:[1,0,1]
	v_pk_fma_f32 v[26:27], v[8:9], v[34:35], v[26:27] op_sel:[0,1,0] op_sel_hi:[1,1,1]
	v_pk_mul_f32 v[22:23], v[38:39], v[20:21] op_sel:[0,0] op_sel_hi:[1,0]
	v_pk_fma_f32 v[10:11], v[10:11], v[40:41], v[22:23] op_sel_hi:[1,0,1]
	v_pk_fma_f32 v[26:27], v[10:11], v[36:37], v[26:27] op_sel:[0,0,0] op_sel_hi:[1,0,1]
	v_pk_mul_f32 v[24:25], v[38:39], v[20:21] op_sel:[0,1] op_sel_hi:[1,1]
	v_pk_fma_f32 v[12:13], v[12:13], v[40:41], v[24:25] op_sel_hi:[1,0,1]
	v_pk_fma_f32 v[26:27], v[12:13], v[36:37], v[26:27] op_sel:[0,1,0] op_sel_hi:[1,1,1]
	v_pk_fma_f32 v[14:15], v[14:15], v[40:41], v[18:19] op_sel_hi:[1,0,1]
	v_pk_fma_f32 v[16:17], v[16:17], v[40:41], v[20:21] op_sel_hi:[1,0,1]
	v_add_f32_dpp v26, v26, v26 row_ror:8 row_mask:0xf bank_mask:0x3 bound_ctrl:1
	v_add_f32_dpp v26, v27, v27 row_ror:8 row_mask:0xf bank_mask:0xc bound_ctrl:1
	ds_read_b128 v[54:57], v1 offset:14928
	ds_read_b128 v[44:47], v2 offset:11008
	v_add_f32_dpp v26, v26, v26 row_half_mirror row_mask:0xf bank_mask:0xf bound_ctrl:1
	ds_read_b64 v[52:53], v3 offset:13824
	ds_read_b128 v[48:51], v2 offset:11264
	v_add_f32_dpp v26, v26, v26 quad_perm:[1,0,3,2] row_mask:0xf bank_mask:0xf bound_ctrl:1
	s_add_u32 s14, s14, 0x1000
	s_addc_u32 s15, s15, 0
	v_add_f32_dpp v26, v26, v26 quad_perm:[2,3,0,1] row_mask:0xf bank_mask:0xf bound_ctrl:1
	s_cmp_eq_u32 s21, 4
	s_cbranch_scc1 .Lml2_den0_4
.Lml2_back0_4:
	v_cvt_pk_bf16_f32 v28, v26, v26
	s_mov_b64 exec, s[18:19]
	global_store_short v58, v28, s[14:15] offset:-4096
	s_mov_b64 exec, -1
	s_waitcnt lgkmcnt(2)
	v_pk_mul_f32 v[18:19], v[44:45], v[54:55] op_sel:[0,1] op_sel_hi:[1,1]
	v_pk_mul_f32 v[20:21], v[46:47], v[54:55] op_sel:[0,1] op_sel_hi:[1,1]
	s_waitcnt lgkmcnt(1)
	v_pk_mul_f32 v[22:23], v[52:53], v[18:19] op_sel:[0,0] op_sel_hi:[1,0]
	v_pk_fma_f32 v[6:7], v[6:7], v[54:55], v[22:23] op_sel_hi:[1,0,1]
	s_waitcnt lgkmcnt(0)
	v_pk_mul_f32 v[26:27], v[6:7], v[48:49] op_sel_hi:[1,0]
	v_pk_mul_f32 v[24:25], v[52:53], v[18:19] op_sel:[0,1] op_sel_hi:[1,1]
	v_pk_fma_f32 v[8:9], v[8:9], v[54:55], v[24:25] op_sel_hi:[1,0,1]
	v_pk_fma_f32 v[26:27], v[8:9], v[48:49], v[26:27] op_sel:[0,1,0] op_sel_hi:[1,1,1]
	v_pk_mul_f32 v[22:23], v[52:53], v[20:21] op_sel:[0,0] op_sel_hi:[1,0]
	v_pk_fma_f32 v[10:11], v[10:11], v[54:55], v[22:23] op_sel_hi:[1,0,1]
	v_pk_fma_f32 v[26:27], v[10:11], v[50:51], v[26:27] op_sel:[0,0,0] op_sel_hi:[1,0,1]
	v_pk_mul_f32 v[24:25], v[52:53], v[20:21] op_sel:[0,1] op_sel_hi:[1,1]
	v_pk_fma_f32 v[12:13], v[12:13], v[54:55], v[24:25] op_sel_hi:[1,0,1]
	v_pk_fma_f32 v[26:27], v[12:13], v[50:51], v[26:27] op_sel:[0,1,0] op_sel_hi:[1,1,1]
	v_pk_fma_f32 v[14:15], v[14:15], v[54:55], v[18:19] op_sel_hi:[1,0,1]
	v_pk_fma_f32 v[16:17], v[16:17], v[54:55], v[20:21] op_sel_hi:[1,0,1]
	v_add_f32_dpp v26, v26, v26 row_ror:8 row_mask:0xf bank_mask:0x3 bound_ctrl:1
	v_add_f32_dpp v26, v27, v27 row_ror:8 row_mask:0xf bank_mask:0xc bound_ctrl:1
	ds_read_b128 v[40:43], v1 offset:14944
	ds_read_b128 v[30:33], v2 offset:11520
	v_add_f32_dpp v26, v26, v26 row_half_mirror row_mask:0xf bank_mask:0xf bound_ctrl:1
	ds_read_b64 v[38:39], v3 offset:14080
	ds_read_b128 v[34:37], v2 offset:11776
	v_add_f32_dpp v26, v26, v26 quad_perm:[1,0,3,2] row_mask:0xf bank_mask:0xf bound_ctrl:1
	s_add_u32 s14, s14, 0x1000
	s_addc_u32 s15, s15, 0
	v_add_f32_dpp v26, v26, v26 quad_perm:[2,3,0,1] row_mask:0xf bank_mask:0xf bound_ctrl:1
	s_cmp_eq_u32 s21, 5
	s_cbranch_scc1 .Lml2_den0_5
.Lml2_back0_5:
	v_cvt_pk_bf16_f32 v28, v26, v26
	s_mov_b64 exec, s[18:19]
	global_store_short v58, v28, s[14:15] offset:-4096
	s_mov_b64 exec, -1
	s_waitcnt lgkmcnt(2)
	v_pk_mul_f32 v[18:19], v[30:31], v[40:41] op_sel:[0,1] op_sel_hi:[1,1]
	v_pk_mul_f32 v[20:21], v[32:33], v[40:41] op_sel:[0,1] op_sel_hi:[1,1]
	s_waitcnt lgkmcnt(1)
	v_pk_mul_f32 v[22:23], v[38:39], v[18:19] op_sel:[0,0] op_sel_hi:[1,0]
	v_pk_fma_f32 v[6:7], v[6:7], v[40:41], v[22:23] op_sel_hi:[1,0,1]
	s_waitcnt lgkmcnt(0)
	v_pk_mul_f32 v[26:27], v[6:7], v[34:35] op_sel_hi:[1,0]
	v_pk_mul_f32 v[24:25], v[38:39], v[18:19] op_sel:[0,1] op_sel_hi:[1,1]
	v_pk_fma_f32 v[8:9], v[8:9], v[40:41], v[24:25] op_sel_hi:[1,0,1]
	v_pk_fma_f32 v[26:27], v[8:9], v[34:35], v[26:27] op_sel:[0,1,0] op_sel_hi:[1,1,1]
	v_pk_mul_f32 v[22:23], v[38:39], v[20:21] op_sel:[0,0] op_sel_hi:[1,0]
	v_pk_fma_f32 v[10:11], v[10:11], v[40:41], v[22:23] op_sel_hi:[1,0,1]
	v_pk_fma_f32 v[26:27], v[10:11], v[36:37], v[26:27] op_sel:[0,0,0] op_sel_hi:[1,0,1]
	v_pk_mul_f32 v[24:25], v[38:39], v[20:21] op_sel:[0,1] op_sel_hi:[1,1]
	v_pk_fma_f32 v[12:13], v[12:13], v[40:41], v[24:25] op_sel_hi:[1,0,1]
	v_pk_fma_f32 v[26:27], v[12:13], v[36:37], v[26:27] op_sel:[0,1,0] op_sel_hi:[1,1,1]
	v_pk_fma_f32 v[14:15], v[14:15], v[40:41], v[18:19] op_sel_hi:[1,0,1]
	v_pk_fma_f32 v[16:17], v[16:17], v[40:41], v[20:21] op_sel_hi:[1,0,1]
	v_add_f32_dpp v26, v26, v26 row_ror:8 row_mask:0xf bank_mask:0x3 bound_ctrl:1
	v_add_f32_dpp v26, v27, v27 row_ror:8 row_mask:0xf bank_mask:0xc bound_ctrl:1
	ds_read_b128 v[54:57], v1 offset:14960
	ds_read_b128 v[44:47], v2 offset:12032
	v_add_f32_dpp v26, v26, v26 row_half_mirror row_mask:0xf bank_mask:0xf bound_ctrl:1
	ds_read_b64 v[52:53], v3 offset:14336
	ds_read_b128 v[48:51], v2 offset:12288
	v_add_f32_dpp v26, v26, v26 quad_perm:[1,0,3,2] row_mask:0xf bank_mask:0xf bound_ctrl:1
	s_add_u32 s14, s14, 0x1000
	s_addc_u32 s15, s15, 0
	v_add_f32_dpp v26, v26, v26 quad_perm:[2,3,0,1] row_mask:0xf bank_mask:0xf bound_ctrl:1
	s_cmp_eq_u32 s21, 6
	s_cbranch_scc1 .Lml2_den0_6
.Lml2_back0_6:
	v_cvt_pk_bf16_f32 v28, v26, v26
	s_mov_b64 exec, s[18:19]
	global_store_short v58, v28, s[14:15] offset:-4096
	s_mov_b64 exec, -1
	s_waitcnt lgkmcnt(2)
	v_pk_mul_f32 v[18:19], v[44:45], v[54:55] op_sel:[0,1] op_sel_hi:[1,1]
	v_pk_mul_f32 v[20:21], v[46:47], v[54:55] op_sel:[0,1] op_sel_hi:[1,1]
	s_waitcnt lgkmcnt(1)
	v_pk_mul_f32 v[22:23], v[52:53], v[18:19] op_sel:[0,0] op_sel_hi:[1,0]
	v_pk_fma_f32 v[6:7], v[6:7], v[54:55], v[22:23] op_sel_hi:[1,0,1]
	s_waitcnt lgkmcnt(0)
	v_pk_mul_f32 v[26:27], v[6:7], v[48:49] op_sel_hi:[1,0]
	v_pk_mul_f32 v[24:25], v[52:53], v[18:19] op_sel:[0,1] op_sel_hi:[1,1]
	v_pk_fma_f32 v[8:9], v[8:9], v[54:55], v[24:25] op_sel_hi:[1,0,1]
	v_pk_fma_f32 v[26:27], v[8:9], v[48:49], v[26:27] op_sel:[0,1,0] op_sel_hi:[1,1,1]
	v_pk_mul_f32 v[22:23], v[52:53], v[20:21] op_sel:[0,0] op_sel_hi:[1,0]
	v_pk_fma_f32 v[10:11], v[10:11], v[54:55], v[22:23] op_sel_hi:[1,0,1]
	v_pk_fma_f32 v[26:27], v[10:11], v[50:51], v[26:27] op_sel:[0,0,0] op_sel_hi:[1,0,1]
	v_pk_mul_f32 v[24:25], v[52:53], v[20:21] op_sel:[0,1] op_sel_hi:[1,1]
	v_pk_fma_f32 v[12:13], v[12:13], v[54:55], v[24:25] op_sel_hi:[1,0,1]
	v_pk_fma_f32 v[26:27], v[12:13], v[50:51], v[26:27] op_sel:[0,1,0] op_sel_hi:[1,1,1]
	v_pk_fma_f32 v[14:15], v[14:15], v[54:55], v[18:19] op_sel_hi:[1,0,1]
	v_pk_fma_f32 v[16:17], v[16:17], v[54:55], v[20:21] op_sel_hi:[1,0,1]
	v_add_f32_dpp v26, v26, v26 row_ror:8 row_mask:0xf bank_mask:0x3 bound_ctrl:1
	v_add_f32_dpp v26, v27, v27 row_ror:8 row_mask:0xf bank_mask:0xc bound_ctrl:1
	ds_read_b128 v[40:43], v1 offset:31232
	ds_read_b128 v[30:33], v2 offset:24832
	v_add_f32_dpp v26, v26, v26 row_half_mirror row_mask:0xf bank_mask:0xf bound_ctrl:1
	ds_read_b64 v[38:39], v3 offset:28928
	ds_read_b128 v[34:37], v2 offset:25088
	v_add_f32_dpp v26, v26, v26 quad_perm:[1,0,3,2] row_mask:0xf bank_mask:0xf bound_ctrl:1
	s_add_u32 s14, s14, 0x1000
	s_addc_u32 s15, s15, 0
	v_add_f32_dpp v26, v26, v26 quad_perm:[2,3,0,1] row_mask:0xf bank_mask:0xf bound_ctrl:1
	s_cmp_eq_u32 s21, 7
	s_cbranch_scc1 .Lml2_den0_7
.Lml2_back0_7:
	v_cvt_pk_bf16_f32 v28, v26, v26
	s_mov_b64 exec, s[18:19]
	global_store_short v58, v28, s[14:15] offset:-4096
	s_mov_b64 exec, -1
	s_waitcnt vmcnt(8)
	v_lshlrev_b32_e32 v88, 16, v80
	v_lshlrev_b32_e32 v89, 16, v81
	v_and_b32_e32 v90, s17, v80
	v_and_b32_e32 v91, s17, v81
	v_lshlrev_b32_e32 v92, 16, v82
	v_and_b32_e32 v93, s17, v82
	v_lshlrev_b32_e32 v94, 16, v83
	v_and_b32_e32 v95, s17, v83
	v_lshlrev_b32_e32 v96, 16, v84
	v_and_b32_e32 v97, s17, v84
	ds_write_b128 v69, v[88:91] offset:33024
	ds_write_b64 v70, v[92:93] offset:33024
	ds_write_b64 v71, v[94:95] offset:33024
	ds_write_b64 v71, v[96:97] offset:33152
	ds_write_b32 v72, v85 offset:33024
	s_cmp_lg_u32 s36, 4
	s_cbranch_scc1 .Lml2_nsc2
	v_mov_b32_e32 v98, v87
	s_nop 1
	v_add_f32_dpp v98, v98, v98 row_shr:1 row_mask:0xf bank_mask:0xf bound_ctrl:1
	s_nop 1
	v_add_f32_dpp v98, v98, v98 row_shr:2 row_mask:0xf bank_mask:0xf bound_ctrl:1
	s_nop 1
	v_add_f32_dpp v98, v98, v98 row_shr:4 row_mask:0xf bank_mask:0xf bound_ctrl:1
	s_nop 1
	v_sub_f32_e32 v99, v86, v98
	s_nop 1
	v_max_f32_dpp v99, v99, v99 row_shr:1 row_mask:0xf bank_mask:0xf
	s_nop 1
	v_max_f32_dpp v99, v99, v99 row_shr:2 row_mask:0xf bank_mask:0xf
	s_nop 1
	v_max_f32_dpp v99, v99, v99 row_shr:4 row_mask:0xf bank_mask:0xf
	s_nop 1
	v_max_f32_e32 v99, v99, v0
	v_add_f32_e32 v103, v98, v99
	v_mov_b32_e32 v105, v0
	s_nop 1
	v_mov_b32_dpp v105, v103 row_shr:1 row_mask:0xf bank_mask:0xf
	v_sub_f32_e32 v104, v86, v103
	v_add_f32_e32 v105, v87, v105
	v_fma_f32 v104, v104, s29, v29
	v_sub_f32_e32 v105, v105, v103
	v_exp_f32_e32 v101, v104
	v_mul_f32_e32 v105, s29, v105
	v_mul_f32_e32 v104, 0xbfb8aa3b, v103
	v_exp_f32_e32 v100, v105
	v_exp_f32_e32 v102, v104
	v_readlane_b32 s4, v103, 7
	s_nop 3
	v_mov_b32_e32 v0, s4
	ds_write_b128 v73, v[100:103] offset:33024

.Lml2_back1_0:
	v_cvt_pk_bf16_f32 v28, v26, v26
	s_mov_b64 exec, s[18:19]
	global_store_short v58, v28, s[14:15] offset:-4096
	s_mov_b64 exec, -1
	s_waitcnt lgkmcnt(2)
	v_pk_mul_f32 v[18:19], v[44:45], v[54:55] op_sel:[0,1] op_sel_hi:[1,1]
	v_pk_mul_f32 v[20:21], v[46:47], v[54:55] op_sel:[0,1] op_sel_hi:[1,1]
	s_waitcnt lgkmcnt(1)
	v_pk_mul_f32 v[22:23], v[52:53], v[18:19] op_sel:[0,0] op_sel_hi:[1,0]
	v_pk_fma_f32 v[6:7], v[6:7], v[54:55], v[22:23] op_sel_hi:[1,0,1]
	s_waitcnt lgkmcnt(0)
	v_pk_mul_f32 v[26:27], v[6:7], v[48:49] op_sel_hi:[1,0]
	v_pk_mul_f32 v[24:25], v[52:53], v[18:19] op_sel:[0,1] op_sel_hi:[1,1]
	v_pk_fma_f32 v[8:9], v[8:9], v[54:55], v[24:25] op_sel_hi:[1,0,1]
	v_pk_fma_f32 v[26:27], v[8:9], v[48:49], v[26:27] op_sel:[0,1,0] op_sel_hi:[1,1,1]
	v_pk_mul_f32 v[22:23], v[52:53], v[20:21] op_sel:[0,0] op_sel_hi:[1,0]
	v_pk_fma_f32 v[10:11], v[10:11], v[54:55], v[22:23] op_sel_hi:[1,0,1]
	v_pk_fma_f32 v[26:27], v[10:11], v[50:51], v[26:27] op_sel:[0,0,0] op_sel_hi:[1,0,1]
	v_pk_mul_f32 v[24:25], v[52:53], v[20:21] op_sel:[0,1] op_sel_hi:[1,1]
	v_pk_fma_f32 v[12:13], v[12:13], v[54:55], v[24:25] op_sel_hi:[1,0,1]
	v_pk_fma_f32 v[26:27], v[12:13], v[50:51], v[26:27] op_sel:[0,1,0] op_sel_hi:[1,1,1]
	v_pk_fma_f32 v[14:15], v[14:15], v[54:55], v[18:19] op_sel_hi:[1,0,1]
	v_pk_fma_f32 v[16:17], v[16:17], v[54:55], v[20:21] op_sel_hi:[1,0,1]
	v_add_f32_dpp v26, v26, v26 row_ror:8 row_mask:0xf bank_mask:0x3 bound_ctrl:1
	v_add_f32_dpp v26, v27, v27 row_ror:8 row_mask:0xf bank_mask:0xc bound_ctrl:1
	ds_read_b128 v[40:43], v1 offset:31264
	ds_read_b128 v[30:33], v2 offset:25856
	v_add_f32_dpp v26, v26, v26 row_half_mirror row_mask:0xf bank_mask:0xf bound_ctrl:1
	ds_read_b64 v[38:39], v3 offset:29440
	ds_read_b128 v[34:37], v2 offset:26112
	v_add_f32_dpp v26, v26, v26 quad_perm:[1,0,3,2] row_mask:0xf bank_mask:0xf bound_ctrl:1
	s_add_u32 s14, s14, 0x1000
	s_addc_u32 s15, s15, 0
	v_add_f32_dpp v26, v26, v26 quad_perm:[2,3,0,1] row_mask:0xf bank_mask:0xf bound_ctrl:1
	s_cmp_eq_u32 s21, 1
	s_cbranch_scc1 .Lml2_den1_1
.Lml2_back1_1:
	v_cvt_pk_bf16_f32 v28, v26, v26
	s_mov_b64 exec, s[18:19]
	global_store_short v58, v28, s[14:15] offset:-4096
	s_mov_b64 exec, -1
	s_waitcnt lgkmcnt(2)
	v_pk_mul_f32 v[18:19], v[30:31], v[40:41] op_sel:[0,1] op_sel_hi:[1,1]
	v_pk_mul_f32 v[20:21], v[32:33], v[40:41] op_sel:[0,1] op_sel_hi:[1,1]
	s_waitcnt lgkmcnt(1)
	v_pk_mul_f32 v[22:23], v[38:39], v[18:19] op_sel:[0,0] op_sel_hi:[1,0]
	v_pk_fma_f32 v[6:7], v[6:7], v[40:41], v[22:23] op_sel_hi:[1,0,1]
	s_waitcnt lgkmcnt(0)
	v_pk_mul_f32 v[26:27], v[6:7], v[34:35] op_sel_hi:[1,0]
	v_pk_mul_f32 v[24:25], v[38:39], v[18:19] op_sel:[0,1] op_sel_hi:[1,1]
	v_pk_fma_f32 v[8:9], v[8:9], v[40:41], v[24:25] op_sel_hi:[1,0,1]
	v_pk_fma_f32 v[26:27], v[8:9], v[34:35], v[26:27] op_sel:[0,1,0] op_sel_hi:[1,1,1]
	v_pk_mul_f32 v[22:23], v[38:39], v[20:21] op_sel:[0,0] op_sel_hi:[1,0]
	v_pk_fma_f32 v[10:11], v[10:11], v[40:41], v[22:23] op_sel_hi:[1,0,1]
	v_pk_fma_f32 v[26:27], v[10:11], v[36:37], v[26:27] op_sel:[0,0,0] op_sel_hi:[1,0,1]
	v_pk_mul_f32 v[24:25], v[38:39], v[20:21] op_sel:[0,1] op_sel_hi:[1,1]
	v_pk_fma_f32 v[12:13], v[12:13], v[40:41], v[24:25] op_sel_hi:[1,0,1]
	v_pk_fma_f32 v[26:27], v[12:13], v[36:37], v[26:27] op_sel:[0,1,0] op_sel_hi:[1,1,1]
	v_pk_fma_f32 v[14:15], v[14:15], v[40:41], v[18:19] op_sel_hi:[1,0,1]
	v_pk_fma_f32 v[16:17], v[16:17], v[40:41], v[20:21] op_sel_hi:[1,0,1]
	v_add_f32_dpp v26, v26, v26 row_ror:8 row_mask:0xf bank_mask:0x3 bound_ctrl:1
	v_add_f32_dpp v26, v27, v27 row_ror:8 row_mask:0xf bank_mask:0xc bound_ctrl:1
	ds_read_b128 v[54:57], v1 offset:31280
	ds_read_b128 v[44:47], v2 offset:26368
	v_add_f32_dpp v26, v26, v26 row_half_mirror row_mask:0xf bank_mask:0xf bound_ctrl:1
	ds_read_b64 v[52:53], v3 offset:29696
	ds_read_b128 v[48:51], v2 offset:26624
	v_add_f32_dpp v26, v26, v26 quad_perm:[1,0,3,2] row_mask:0xf bank_mask:0xf bound_ctrl:1
	s_add_u32 s14, s14, 0x1000
	s_addc_u32 s15, s15, 0
	v_add_f32_dpp v26, v26, v26 quad_perm:[2,3,0,1] row_mask:0xf bank_mask:0xf bound_ctrl:1
	s_cmp_eq_u32 s21, 2
	s_cbranch_scc1 .Lml2_den1_2
.Lml2_back1_2:
	v_cvt_pk_bf16_f32 v28, v26, v26
	s_mov_b64 exec, s[18:19]
	global_store_short v58, v28, s[14:15] offset:-4096
	s_mov_b64 exec, -1
	s_waitcnt lgkmcnt(2)
	v_pk_mul_f32 v[18:19], v[44:45], v[54:55] op_sel:[0,1] op_sel_hi:[1,1]
	v_pk_mul_f32 v[20:21], v[46:47], v[54:55] op_sel:[0,1] op_sel_hi:[1,1]
	s_waitcnt lgkmcnt(1)
	v_pk_mul_f32 v[22:23], v[52:53], v[18:19] op_sel:[0,0] op_sel_hi:[1,0]
	v_pk_fma_f32 v[6:7], v[6:7], v[54:55], v[22:23] op_sel_hi:[1,0,1]
	s_waitcnt lgkmcnt(0)
	v_pk_mul_f32 v[26:27], v[6:7], v[48:49] op_sel_hi:[1,0]
	v_pk_mul_f32 v[24:25], v[52:53], v[18:19] op_sel:[0,1] op_sel_hi:[1,1]
	v_pk_fma_f32 v[8:9], v[8:9], v[54:55], v[24:25] op_sel_hi:[1,0,1]
	v_pk_fma_f32 v[26:27], v[8:9], v[48:49], v[26:27] op_sel:[0,1,0] op_sel_hi:[1,1,1]
	v_pk_mul_f32 v[22:23], v[52:53], v[20:21] op_sel:[0,0] op_sel_hi:[1,0]
	v_pk_fma_f32 v[10:11], v[10:11], v[54:55], v[22:23] op_sel_hi:[1,0,1]
	v_pk_fma_f32 v[26:27], v[10:11], v[50:51], v[26:27] op_sel:[0,0,0] op_sel_hi:[1,0,1]
	v_pk_mul_f32 v[24:25], v[52:53], v[20:21] op_sel:[0,1] op_sel_hi:[1,1]
	v_pk_fma_f32 v[12:13], v[12:13], v[54:55], v[24:25] op_sel_hi:[1,0,1]
	v_pk_fma_f32 v[26:27], v[12:13], v[50:51], v[26:27] op_sel:[0,1,0] op_sel_hi:[1,1,1]
	v_pk_fma_f32 v[14:15], v[14:15], v[54:55], v[18:19] op_sel_hi:[1,0,1]
	v_pk_fma_f32 v[16:17], v[16:17], v[54:55], v[20:21] op_sel_hi:[1,0,1]
	v_add_f32_dpp v26, v26, v26 row_ror:8 row_mask:0xf bank_mask:0x3 bound_ctrl:1
	v_add_f32_dpp v26, v27, v27 row_ror:8 row_mask:0xf bank_mask:0xc bound_ctrl:1
	ds_read_b128 v[40:43], v1 offset:31296
	ds_read_b128 v[30:33], v2 offset:26880
	v_add_f32_dpp v26, v26, v26 row_half_mirror row_mask:0xf bank_mask:0xf bound_ctrl:1
	ds_read_b64 v[38:39], v3 offset:29952
	ds_read_b128 v[34:37], v2 offset:27136
	v_add_f32_dpp v26, v26, v26 quad_perm:[1,0,3,2] row_mask:0xf bank_mask:0xf bound_ctrl:1
	s_add_u32 s14, s14, 0x1000
	s_addc_u32 s15, s15, 0
	v_add_f32_dpp v26, v26, v26 quad_perm:[2,3,0,1] row_mask:0xf bank_mask:0xf bound_ctrl:1
	s_cmp_eq_u32 s21, 3
	s_cbranch_scc1 .Lml2_den1_3
.Lml2_back1_3:
	v_cvt_pk_bf16_f32 v28, v26, v26
	s_mov_b64 exec, s[18:19]
	global_store_short v58, v28, s[14:15] offset:-4096
	s_mov_b64 exec, -1
	s_waitcnt lgkmcnt(2)
	v_pk_mul_f32 v[18:19], v[30:31], v[40:41] op_sel:[0,1] op_sel_hi:[1,1]
	v_pk_mul_f32 v[20:21], v[32:33], v[40:41] op_sel:[0,1] op_sel_hi:[1,1]
	s_waitcnt lgkmcnt(1)
	v_pk_mul_f32 v[22:23], v[38:39], v[18:19] op_sel:[0,0] op_sel_hi:[1,0]
	v_pk_fma_f32 v[6:7], v[6:7], v[40:41], v[22:23] op_sel_hi:[1,0,1]
	s_waitcnt lgkmcnt(0)
	v_pk_mul_f32 v[26:27], v[6:7], v[34:35] op_sel_hi:[1,0]
	v_pk_mul_f32 v[24:25], v[38:39], v[18:19] op_sel:[0,1] op_sel_hi:[1,1]
	v_pk_fma_f32 v[8:9], v[8:9], v[40:41], v[24:25] op_sel_hi:[1,0,1]
	v_pk_fma_f32 v[26:27], v[8:9], v[34:35], v[26:27] op_sel:[0,1,0] op_sel_hi:[1,1,1]
	v_pk_mul_f32 v[22:23], v[38:39], v[20:21] op_sel:[0,0] op_sel_hi:[1,0]
	v_pk_fma_f32 v[10:11], v[10:11], v[40:41], v[22:23] op_sel_hi:[1,0,1]
	v_pk_fma_f32 v[26:27], v[10:11], v[36:37], v[26:27] op_sel:[0,0,0] op_sel_hi:[1,0,1]
	v_pk_mul_f32 v[24:25], v[38:39], v[20:21] op_sel:[0,1] op_sel_hi:[1,1]
	v_pk_fma_f32 v[12:13], v[12:13], v[40:41], v[24:25] op_sel_hi:[1,0,1]
	v_pk_fma_f32 v[26:27], v[12:13], v[36:37], v[26:27] op_sel:[0,1,0] op_sel_hi:[1,1,1]
	v_pk_fma_f32 v[14:15], v[14:15], v[40:41], v[18:19] op_sel_hi:[1,0,1]
	v_pk_fma_f32 v[16:17], v[16:17], v[40:41], v[20:21] op_sel_hi:[1,0,1]
	v_add_f32_dpp v26, v26, v26 row_ror:8 row_mask:0xf bank_mask:0x3 bound_ctrl:1
	v_add_f32_dpp v26, v27, v27 row_ror:8 row_mask:0xf bank_mask:0xc bound_ctrl:1
	ds_read_b128 v[54:57], v1 offset:31312
	ds_read_b128 v[44:47], v2 offset:27392
	v_add_f32_dpp v26, v26, v26 row_half_mirror row_mask:0xf bank_mask:0xf bound_ctrl:1
	ds_read_b64 v[52:53], v3 offset:30208
	ds_read_b128 v[48:51], v2 offset:27648
	v_add_f32_dpp v26, v26, v26 quad_perm:[1,0,3,2] row_mask:0xf bank_mask:0xf bound_ctrl:1
	s_add_u32 s14, s14, 0x1000
	s_addc_u32 s15, s15, 0
	v_add_f32_dpp v26, v26, v26 quad_perm:[2,3,0,1] row_mask:0xf bank_mask:0xf bound_ctrl:1
	s_cmp_eq_u32 s21, 4
	s_cbranch_scc1 .Lml2_den1_4
.Lml2_back1_4:
	v_cvt_pk_bf16_f32 v28, v26, v26
	s_mov_b64 exec, s[18:19]
	global_store_short v58, v28, s[14:15] offset:-4096
	s_mov_b64 exec, -1
	s_waitcnt lgkmcnt(2)
	v_pk_mul_f32 v[18:19], v[44:45], v[54:55] op_sel:[0,1] op_sel_hi:[1,1]
	v_pk_mul_f32 v[20:21], v[46:47], v[54:55] op_sel:[0,1] op_sel_hi:[1,1]
	s_waitcnt lgkmcnt(1)
	v_pk_mul_f32 v[22:23], v[52:53], v[18:19] op_sel:[0,0] op_sel_hi:[1,0]
	v_pk_fma_f32 v[6:7], v[6:7], v[54:55], v[22:23] op_sel_hi:[1,0,1]
	s_waitcnt lgkmcnt(0)
	v_pk_mul_f32 v[26:27], v[6:7], v[48:49] op_sel_hi:[1,0]
	v_pk_mul_f32 v[24:25], v[52:53], v[18:19] op_sel:[0,1] op_sel_hi:[1,1]
	v_pk_fma_f32 v[8:9], v[8:9], v[54:55], v[24:25] op_sel_hi:[1,0,1]
	v_pk_fma_f32 v[26:27], v[8:9], v[48:49], v[26:27] op_sel:[0,1,0] op_sel_hi:[1,1,1]
	v_pk_mul_f32 v[22:23], v[52:53], v[20:21] op_sel:[0,0] op_sel_hi:[1,0]
	v_pk_fma_f32 v[10:11], v[10:11], v[54:55], v[22:23] op_sel_hi:[1,0,1]
	v_pk_fma_f32 v[26:27], v[10:11], v[50:51], v[26:27] op_sel:[0,0,0] op_sel_hi:[1,0,1]
	v_pk_mul_f32 v[24:25], v[52:53], v[20:21] op_sel:[0,1] op_sel_hi:[1,1]
	v_pk_fma_f32 v[12:13], v[12:13], v[54:55], v[24:25] op_sel_hi:[1,0,1]
	v_pk_fma_f32 v[26:27], v[12:13], v[50:51], v[26:27] op_sel:[0,1,0] op_sel_hi:[1,1,1]
	v_pk_fma_f32 v[14:15], v[14:15], v[54:55], v[18:19] op_sel_hi:[1,0,1]
	v_pk_fma_f32 v[16:17], v[16:17], v[54:55], v[20:21] op_sel_hi:[1,0,1]
	v_add_f32_dpp v26, v26, v26 row_ror:8 row_mask:0xf bank_mask:0x3 bound_ctrl:1
	v_add_f32_dpp v26, v27, v27 row_ror:8 row_mask:0xf bank_mask:0xc bound_ctrl:1
	ds_read_b128 v[40:43], v1 offset:31328
	ds_read_b128 v[30:33], v2 offset:27904
	v_add_f32_dpp v26, v26, v26 row_half_mirror row_mask:0xf bank_mask:0xf bound_ctrl:1
	ds_read_b64 v[38:39], v3 offset:30464
	ds_read_b128 v[34:37], v2 offset:28160
	v_add_f32_dpp v26, v26, v26 quad_perm:[1,0,3,2] row_mask:0xf bank_mask:0xf bound_ctrl:1
	s_add_u32 s14, s14, 0x1000
	s_addc_u32 s15, s15, 0
	v_add_f32_dpp v26, v26, v26 quad_perm:[2,3,0,1] row_mask:0xf bank_mask:0xf bound_ctrl:1
	s_cmp_eq_u32 s21, 5
	s_cbranch_scc1 .Lml2_den1_5
.Lml2_back1_5:
	v_cvt_pk_bf16_f32 v28, v26, v26
	s_mov_b64 exec, s[18:19]
	global_store_short v58, v28, s[14:15] offset:-4096
	s_mov_b64 exec, -1
	s_waitcnt lgkmcnt(2)
	v_pk_mul_f32 v[18:19], v[30:31], v[40:41] op_sel:[0,1] op_sel_hi:[1,1]
	v_pk_mul_f32 v[20:21], v[32:33], v[40:41] op_sel:[0,1] op_sel_hi:[1,1]
	s_waitcnt lgkmcnt(1)
	v_pk_mul_f32 v[22:23], v[38:39], v[18:19] op_sel:[0,0] op_sel_hi:[1,0]
	v_pk_fma_f32 v[6:7], v[6:7], v[40:41], v[22:23] op_sel_hi:[1,0,1]
	s_waitcnt lgkmcnt(0)
	v_pk_mul_f32 v[26:27], v[6:7], v[34:35] op_sel_hi:[1,0]
	v_pk_mul_f32 v[24:25], v[38:39], v[18:19] op_sel:[0,1] op_sel_hi:[1,1]
	v_pk_fma_f32 v[8:9], v[8:9], v[40:41], v[24:25] op_sel_hi:[1,0,1]
	v_pk_fma_f32 v[26:27], v[8:9], v[34:35], v[26:27] op_sel:[0,1,0] op_sel_hi:[1,1,1]
	v_pk_mul_f32 v[22:23], v[38:39], v[20:21] op_sel:[0,0] op_sel_hi:[1,0]
	v_pk_fma_f32 v[10:11], v[10:11], v[40:41], v[22:23] op_sel_hi:[1,0,1]
	v_pk_fma_f32 v[26:27], v[10:11], v[36:37], v[26:27] op_sel:[0,0,0] op_sel_hi:[1,0,1]
	v_pk_mul_f32 v[24:25], v[38:39], v[20:21] op_sel:[0,1] op_sel_hi:[1,1]
	v_pk_fma_f32 v[12:13], v[12:13], v[40:41], v[24:25] op_sel_hi:[1,0,1]
	v_pk_fma_f32 v[26:27], v[12:13], v[36:37], v[26:27] op_sel:[0,1,0] op_sel_hi:[1,1,1]
	v_pk_fma_f32 v[14:15], v[14:15], v[40:41], v[18:19] op_sel_hi:[1,0,1]
	v_pk_fma_f32 v[16:17], v[16:17], v[40:41], v[20:21] op_sel_hi:[1,0,1]
	v_add_f32_dpp v26, v26, v26 row_ror:8 row_mask:0xf bank_mask:0x3 bound_ctrl:1
	v_add_f32_dpp v26, v27, v27 row_ror:8 row_mask:0xf bank_mask:0xc bound_ctrl:1
	ds_read_b128 v[54:57], v1 offset:31344
	ds_read_b128 v[44:47], v2 offset:28416
	v_add_f32_dpp v26, v26, v26 row_half_mirror row_mask:0xf bank_mask:0xf bound_ctrl:1
	ds_read_b64 v[52:53], v3 offset:30720
	ds_read_b128 v[48:51], v2 offset:28672
	v_add_f32_dpp v26, v26, v26 quad_perm:[1,0,3,2] row_mask:0xf bank_mask:0xf bound_ctrl:1
	s_add_u32 s14, s14, 0x1000
	s_addc_u32 s15, s15, 0
	v_add_f32_dpp v26, v26, v26 quad_perm:[2,3,0,1] row_mask:0xf bank_mask:0xf bound_ctrl:1
	s_cmp_eq_u32 s21, 6
	s_cbranch_scc1 .Lml2_den1_6
.Lml2_back1_6:
	v_cvt_pk_bf16_f32 v28, v26, v26
	s_mov_b64 exec, s[18:19]
	global_store_short v58, v28, s[14:15] offset:-4096
	s_mov_b64 exec, -1
	s_waitcnt lgkmcnt(2)
	v_pk_mul_f32 v[18:19], v[44:45], v[54:55] op_sel:[0,1] op_sel_hi:[1,1]
	v_pk_mul_f32 v[20:21], v[46:47], v[54:55] op_sel:[0,1] op_sel_hi:[1,1]
	s_waitcnt lgkmcnt(1)
	v_pk_mul_f32 v[22:23], v[52:53], v[18:19] op_sel:[0,0] op_sel_hi:[1,0]
	v_pk_fma_f32 v[6:7], v[6:7], v[54:55], v[22:23] op_sel_hi:[1,0,1]
	s_waitcnt lgkmcnt(0)
	v_pk_mul_f32 v[26:27], v[6:7], v[48:49] op_sel_hi:[1,0]
	v_pk_mul_f32 v[24:25], v[52:53], v[18:19] op_sel:[0,1] op_sel_hi:[1,1]
	v_pk_fma_f32 v[8:9], v[8:9], v[54:55], v[24:25] op_sel_hi:[1,0,1]
	v_pk_fma_f32 v[26:27], v[8:9], v[48:49], v[26:27] op_sel:[0,1,0] op_sel_hi:[1,1,1]
	v_pk_mul_f32 v[22:23], v[52:53], v[20:21] op_sel:[0,0] op_sel_hi:[1,0]
	v_pk_fma_f32 v[10:11], v[10:11], v[54:55], v[22:23] op_sel_hi:[1,0,1]
	v_pk_fma_f32 v[26:27], v[10:11], v[50:51], v[26:27] op_sel:[0,0,0] op_sel_hi:[1,0,1]
	v_pk_mul_f32 v[24:25], v[52:53], v[20:21] op_sel:[0,1] op_sel_hi:[1,1]
	v_pk_fma_f32 v[12:13], v[12:13], v[54:55], v[24:25] op_sel_hi:[1,0,1]
	v_pk_fma_f32 v[26:27], v[12:13], v[50:51], v[26:27] op_sel:[0,1,0] op_sel_hi:[1,1,1]
	v_pk_fma_f32 v[14:15], v[14:15], v[54:55], v[18:19] op_sel_hi:[1,0,1]
	v_pk_fma_f32 v[16:17], v[16:17], v[54:55], v[20:21] op_sel_hi:[1,0,1]
	v_add_f32_dpp v26, v26, v26 row_ror:8 row_mask:0xf bank_mask:0x3 bound_ctrl:1
	v_add_f32_dpp v26, v27, v27 row_ror:8 row_mask:0xf bank_mask:0xc bound_ctrl:1
	ds_read_b128 v[40:43], v1 offset:47616
	ds_read_b128 v[30:33], v2 offset:41216
	v_add_f32_dpp v26, v26, v26 row_half_mirror row_mask:0xf bank_mask:0xf bound_ctrl:1
	ds_read_b64 v[38:39], v3 offset:45312
	ds_read_b128 v[34:37], v2 offset:41472
	v_add_f32_dpp v26, v26, v26 quad_perm:[1,0,3,2] row_mask:0xf bank_mask:0xf bound_ctrl:1
	s_add_u32 s14, s14, 0x1000
	s_addc_u32 s15, s15, 0
	v_add_f32_dpp v26, v26, v26 quad_perm:[2,3,0,1] row_mask:0xf bank_mask:0xf bound_ctrl:1
	s_cmp_eq_u32 s21, 7
	s_cbranch_scc1 .Lml2_den1_7
.Lml2_back1_7:
	v_cvt_pk_bf16_f32 v28, v26, v26
	s_mov_b64 exec, s[18:19]
	global_store_short v58, v28, s[14:15] offset:-4096
	s_mov_b64 exec, -1
	s_waitcnt vmcnt(8)
	v_lshlrev_b32_e32 v88, 16, v80
	v_lshlrev_b32_e32 v89, 16, v81
	v_and_b32_e32 v90, s17, v80
	v_and_b32_e32 v91, s17, v81
	v_lshlrev_b32_e32 v92, 16, v82
	v_and_b32_e32 v93, s17, v82
	v_lshlrev_b32_e32 v94, 16, v83
	v_and_b32_e32 v95, s17, v83
	v_lshlrev_b32_e32 v96, 16, v84
	v_and_b32_e32 v97, s17, v84
	ds_write_b128 v69, v[88:91] offset:256
	ds_write_b64 v70, v[92:93] offset:256
	ds_write_b64 v71, v[94:95] offset:256
	ds_write_b64 v71, v[96:97] offset:384
	ds_write_b32 v72, v85 offset:256
	s_cmp_lg_u32 s36, 4
	s_cbranch_scc1 .Lml2_nsc3
	v_mov_b32_e32 v98, v87
	s_nop 1
	v_add_f32_dpp v98, v98, v98 row_shr:1 row_mask:0xf bank_mask:0xf bound_ctrl:1
	s_nop 1
	v_add_f32_dpp v98, v98, v98 row_shr:2 row_mask:0xf bank_mask:0xf bound_ctrl:1
	s_nop 1
	v_add_f32_dpp v98, v98, v98 row_shr:4 row_mask:0xf bank_mask:0xf bound_ctrl:1
	s_nop 1
	v_sub_f32_e32 v99, v86, v98
	s_nop 1
	v_max_f32_dpp v99, v99, v99 row_shr:1 row_mask:0xf bank_mask:0xf
	s_nop 1
	v_max_f32_dpp v99, v99, v99 row_shr:2 row_mask:0xf bank_mask:0xf
	s_nop 1
	v_max_f32_dpp v99, v99, v99 row_shr:4 row_mask:0xf bank_mask:0xf
	s_nop 1
	v_max_f32_e32 v99, v99, v0
	v_add_f32_e32 v103, v98, v99
	v_mov_b32_e32 v105, v0
	s_nop 1
	v_mov_b32_dpp v105, v103 row_shr:1 row_mask:0xf bank_mask:0xf
	v_sub_f32_e32 v104, v86, v103
	v_add_f32_e32 v105, v87, v105
	v_fma_f32 v104, v104, s29, v29
	v_sub_f32_e32 v105, v105, v103
	v_exp_f32_e32 v101, v104
	v_mul_f32_e32 v105, s29, v105
	v_mul_f32_e32 v104, 0xbfb8aa3b, v103
	v_exp_f32_e32 v100, v105
	v_exp_f32_e32 v102, v104
	v_readlane_b32 s4, v103, 7
	s_nop 3
	v_mov_b32_e32 v0, s4
	ds_write_b128 v73, v[100:103] offset:256

.Lml2_back2_0:
	v_cvt_pk_bf16_f32 v28, v26, v26
	s_mov_b64 exec, s[18:19]
	global_store_short v58, v28, s[14:15] offset:-4096
	s_mov_b64 exec, -1
	s_waitcnt lgkmcnt(2)
	v_pk_mul_f32 v[18:19], v[44:45], v[54:55] op_sel:[0,1] op_sel_hi:[1,1]
	v_pk_mul_f32 v[20:21], v[46:47], v[54:55] op_sel:[0,1] op_sel_hi:[1,1]
	s_waitcnt lgkmcnt(1)
	v_pk_mul_f32 v[22:23], v[52:53], v[18:19] op_sel:[0,0] op_sel_hi:[1,0]
	v_pk_fma_f32 v[6:7], v[6:7], v[54:55], v[22:23] op_sel_hi:[1,0,1]
	s_waitcnt lgkmcnt(0)
	v_pk_mul_f32 v[26:27], v[6:7], v[48:49] op_sel_hi:[1,0]
	v_pk_mul_f32 v[24:25], v[52:53], v[18:19] op_sel:[0,1] op_sel_hi:[1,1]
	v_pk_fma_f32 v[8:9], v[8:9], v[54:55], v[24:25] op_sel_hi:[1,0,1]
	v_pk_fma_f32 v[26:27], v[8:9], v[48:49], v[26:27] op_sel:[0,1,0] op_sel_hi:[1,1,1]
	v_pk_mul_f32 v[22:23], v[52:53], v[20:21] op_sel:[0,0] op_sel_hi:[1,0]
	v_pk_fma_f32 v[10:11], v[10:11], v[54:55], v[22:23] op_sel_hi:[1,0,1]
	v_pk_fma_f32 v[26:27], v[10:11], v[50:51], v[26:27] op_sel:[0,0,0] op_sel_hi:[1,0,1]
	v_pk_mul_f32 v[24:25], v[52:53], v[20:21] op_sel:[0,1] op_sel_hi:[1,1]
	v_pk_fma_f32 v[12:13], v[12:13], v[54:55], v[24:25] op_sel_hi:[1,0,1]
	v_pk_fma_f32 v[26:27], v[12:13], v[50:51], v[26:27] op_sel:[0,1,0] op_sel_hi:[1,1,1]
	v_pk_fma_f32 v[14:15], v[14:15], v[54:55], v[18:19] op_sel_hi:[1,0,1]
	v_pk_fma_f32 v[16:17], v[16:17], v[54:55], v[20:21] op_sel_hi:[1,0,1]
	v_add_f32_dpp v26, v26, v26 row_ror:8 row_mask:0xf bank_mask:0x3 bound_ctrl:1
	v_add_f32_dpp v26, v27, v27 row_ror:8 row_mask:0xf bank_mask:0xc bound_ctrl:1
	ds_read_b128 v[40:43], v1 offset:47648
	ds_read_b128 v[30:33], v2 offset:42240
	v_add_f32_dpp v26, v26, v26 row_half_mirror row_mask:0xf bank_mask:0xf bound_ctrl:1
	ds_read_b64 v[38:39], v3 offset:45824
	ds_read_b128 v[34:37], v2 offset:42496
	v_add_f32_dpp v26, v26, v26 quad_perm:[1,0,3,2] row_mask:0xf bank_mask:0xf bound_ctrl:1
	s_add_u32 s14, s14, 0x1000
	s_addc_u32 s15, s15, 0
	v_add_f32_dpp v26, v26, v26 quad_perm:[2,3,0,1] row_mask:0xf bank_mask:0xf bound_ctrl:1
	s_cmp_eq_u32 s21, 1
	s_cbranch_scc1 .Lml2_den2_1
.Lml2_back2_1:
	v_cvt_pk_bf16_f32 v28, v26, v26
	s_mov_b64 exec, s[18:19]
	global_store_short v58, v28, s[14:15] offset:-4096
	s_mov_b64 exec, -1
	s_waitcnt lgkmcnt(2)
	v_pk_mul_f32 v[18:19], v[30:31], v[40:41] op_sel:[0,1] op_sel_hi:[1,1]
	v_pk_mul_f32 v[20:21], v[32:33], v[40:41] op_sel:[0,1] op_sel_hi:[1,1]
	s_waitcnt lgkmcnt(1)
	v_pk_mul_f32 v[22:23], v[38:39], v[18:19] op_sel:[0,0] op_sel_hi:[1,0]
	v_pk_fma_f32 v[6:7], v[6:7], v[40:41], v[22:23] op_sel_hi:[1,0,1]
	s_waitcnt lgkmcnt(0)
	v_pk_mul_f32 v[26:27], v[6:7], v[34:35] op_sel_hi:[1,0]
	v_pk_mul_f32 v[24:25], v[38:39], v[18:19] op_sel:[0,1] op_sel_hi:[1,1]
	v_pk_fma_f32 v[8:9], v[8:9], v[40:41], v[24:25] op_sel_hi:[1,0,1]
	v_pk_fma_f32 v[26:27], v[8:9], v[34:35], v[26:27] op_sel:[0,1,0] op_sel_hi:[1,1,1]
	v_pk_mul_f32 v[22:23], v[38:39], v[20:21] op_sel:[0,0] op_sel_hi:[1,0]
	v_pk_fma_f32 v[10:11], v[10:11], v[40:41], v[22:23] op_sel_hi:[1,0,1]
	v_pk_fma_f32 v[26:27], v[10:11], v[36:37], v[26:27] op_sel:[0,0,0] op_sel_hi:[1,0,1]
	v_pk_mul_f32 v[24:25], v[38:39], v[20:21] op_sel:[0,1] op_sel_hi:[1,1]
	v_pk_fma_f32 v[12:13], v[12:13], v[40:41], v[24:25] op_sel_hi:[1,0,1]
	v_pk_fma_f32 v[26:27], v[12:13], v[36:37], v[26:27] op_sel:[0,1,0] op_sel_hi:[1,1,1]
	v_pk_fma_f32 v[14:15], v[14:15], v[40:41], v[18:19] op_sel_hi:[1,0,1]
	v_pk_fma_f32 v[16:17], v[16:17], v[40:41], v[20:21] op_sel_hi:[1,0,1]
	v_add_f32_dpp v26, v26, v26 row_ror:8 row_mask:0xf bank_mask:0x3 bound_ctrl:1
	v_add_f32_dpp v26, v27, v27 row_ror:8 row_mask:0xf bank_mask:0xc bound_ctrl:1
	ds_read_b128 v[54:57], v1 offset:47664
	ds_read_b128 v[44:47], v2 offset:42752
	v_add_f32_dpp v26, v26, v26 row_half_mirror row_mask:0xf bank_mask:0xf bound_ctrl:1
	ds_read_b64 v[52:53], v3 offset:46080
	ds_read_b128 v[48:51], v2 offset:43008
	v_add_f32_dpp v26, v26, v26 quad_perm:[1,0,3,2] row_mask:0xf bank_mask:0xf bound_ctrl:1
	s_add_u32 s14, s14, 0x1000
	s_addc_u32 s15, s15, 0
	v_add_f32_dpp v26, v26, v26 quad_perm:[2,3,0,1] row_mask:0xf bank_mask:0xf bound_ctrl:1
	s_cmp_eq_u32 s21, 2
	s_cbranch_scc1 .Lml2_den2_2
.Lml2_back2_2:
	v_cvt_pk_bf16_f32 v28, v26, v26
	s_mov_b64 exec, s[18:19]
	global_store_short v58, v28, s[14:15] offset:-4096
	s_mov_b64 exec, -1
	s_waitcnt lgkmcnt(2)
	v_pk_mul_f32 v[18:19], v[44:45], v[54:55] op_sel:[0,1] op_sel_hi:[1,1]
	v_pk_mul_f32 v[20:21], v[46:47], v[54:55] op_sel:[0,1] op_sel_hi:[1,1]
	s_waitcnt lgkmcnt(1)
	v_pk_mul_f32 v[22:23], v[52:53], v[18:19] op_sel:[0,0] op_sel_hi:[1,0]
	v_pk_fma_f32 v[6:7], v[6:7], v[54:55], v[22:23] op_sel_hi:[1,0,1]
	s_waitcnt lgkmcnt(0)
	v_pk_mul_f32 v[26:27], v[6:7], v[48:49] op_sel_hi:[1,0]
	v_pk_mul_f32 v[24:25], v[52:53], v[18:19] op_sel:[0,1] op_sel_hi:[1,1]
	v_pk_fma_f32 v[8:9], v[8:9], v[54:55], v[24:25] op_sel_hi:[1,0,1]
	v_pk_fma_f32 v[26:27], v[8:9], v[48:49], v[26:27] op_sel:[0,1,0] op_sel_hi:[1,1,1]
	v_pk_mul_f32 v[22:23], v[52:53], v[20:21] op_sel:[0,0] op_sel_hi:[1,0]
	v_pk_fma_f32 v[10:11], v[10:11], v[54:55], v[22:23] op_sel_hi:[1,0,1]
	v_pk_fma_f32 v[26:27], v[10:11], v[50:51], v[26:27] op_sel:[0,0,0] op_sel_hi:[1,0,1]
	v_pk_mul_f32 v[24:25], v[52:53], v[20:21] op_sel:[0,1] op_sel_hi:[1,1]
	v_pk_fma_f32 v[12:13], v[12:13], v[54:55], v[24:25] op_sel_hi:[1,0,1]
	v_pk_fma_f32 v[26:27], v[12:13], v[50:51], v[26:27] op_sel:[0,1,0] op_sel_hi:[1,1,1]
	v_pk_fma_f32 v[14:15], v[14:15], v[54:55], v[18:19] op_sel_hi:[1,0,1]
	v_pk_fma_f32 v[16:17], v[16:17], v[54:55], v[20:21] op_sel_hi:[1,0,1]
	v_add_f32_dpp v26, v26, v26 row_ror:8 row_mask:0xf bank_mask:0x3 bound_ctrl:1
	v_add_f32_dpp v26, v27, v27 row_ror:8 row_mask:0xf bank_mask:0xc bound_ctrl:1
	ds_read_b128 v[40:43], v1 offset:47680
	ds_read_b128 v[30:33], v2 offset:43264
	v_add_f32_dpp v26, v26, v26 row_half_mirror row_mask:0xf bank_mask:0xf bound_ctrl:1
	ds_read_b64 v[38:39], v3 offset:46336
	ds_read_b128 v[34:37], v2 offset:43520
	v_add_f32_dpp v26, v26, v26 quad_perm:[1,0,3,2] row_mask:0xf bank_mask:0xf bound_ctrl:1
	s_add_u32 s14, s14, 0x1000
	s_addc_u32 s15, s15, 0
	v_add_f32_dpp v26, v26, v26 quad_perm:[2,3,0,1] row_mask:0xf bank_mask:0xf bound_ctrl:1
	s_cmp_eq_u32 s21, 3
	s_cbranch_scc1 .Lml2_den2_3
.Lml2_back2_3:
	v_cvt_pk_bf16_f32 v28, v26, v26
	s_mov_b64 exec, s[18:19]
	global_store_short v58, v28, s[14:15] offset:-4096
	s_mov_b64 exec, -1
	s_waitcnt lgkmcnt(2)
	v_pk_mul_f32 v[18:19], v[30:31], v[40:41] op_sel:[0,1] op_sel_hi:[1,1]
	v_pk_mul_f32 v[20:21], v[32:33], v[40:41] op_sel:[0,1] op_sel_hi:[1,1]
	s_waitcnt lgkmcnt(1)
	v_pk_mul_f32 v[22:23], v[38:39], v[18:19] op_sel:[0,0] op_sel_hi:[1,0]
	v_pk_fma_f32 v[6:7], v[6:7], v[40:41], v[22:23] op_sel_hi:[1,0,1]
	s_waitcnt lgkmcnt(0)
	v_pk_mul_f32 v[26:27], v[6:7], v[34:35] op_sel_hi:[1,0]
	v_pk_mul_f32 v[24:25], v[38:39], v[18:19] op_sel:[0,1] op_sel_hi:[1,1]
	v_pk_fma_f32 v[8:9], v[8:9], v[40:41], v[24:25] op_sel_hi:[1,0,1]
	v_pk_fma_f32 v[26:27], v[8:9], v[34:35], v[26:27] op_sel:[0,1,0] op_sel_hi:[1,1,1]
	v_pk_mul_f32 v[22:23], v[38:39], v[20:21] op_sel:[0,0] op_sel_hi:[1,0]
	v_pk_fma_f32 v[10:11], v[10:11], v[40:41], v[22:23] op_sel_hi:[1,0,1]
	v_pk_fma_f32 v[26:27], v[10:11], v[36:37], v[26:27] op_sel:[0,0,0] op_sel_hi:[1,0,1]
	v_pk_mul_f32 v[24:25], v[38:39], v[20:21] op_sel:[0,1] op_sel_hi:[1,1]
	v_pk_fma_f32 v[12:13], v[12:13], v[40:41], v[24:25] op_sel_hi:[1,0,1]
	v_pk_fma_f32 v[26:27], v[12:13], v[36:37], v[26:27] op_sel:[0,1,0] op_sel_hi:[1,1,1]
	v_pk_fma_f32 v[14:15], v[14:15], v[40:41], v[18:19] op_sel_hi:[1,0,1]
	v_pk_fma_f32 v[16:17], v[16:17], v[40:41], v[20:21] op_sel_hi:[1,0,1]
	v_add_f32_dpp v26, v26, v26 row_ror:8 row_mask:0xf bank_mask:0x3 bound_ctrl:1
	v_add_f32_dpp v26, v27, v27 row_ror:8 row_mask:0xf bank_mask:0xc bound_ctrl:1
	ds_read_b128 v[54:57], v1 offset:47696
	ds_read_b128 v[44:47], v2 offset:43776
	v_add_f32_dpp v26, v26, v26 row_half_mirror row_mask:0xf bank_mask:0xf bound_ctrl:1
	ds_read_b64 v[52:53], v3 offset:46592
	ds_read_b128 v[48:51], v2 offset:44032
	v_add_f32_dpp v26, v26, v26 quad_perm:[1,0,3,2] row_mask:0xf bank_mask:0xf bound_ctrl:1
	s_add_u32 s14, s14, 0x1000
	s_addc_u32 s15, s15, 0
	v_add_f32_dpp v26, v26, v26 quad_perm:[2,3,0,1] row_mask:0xf bank_mask:0xf bound_ctrl:1
	s_cmp_eq_u32 s21, 4
	s_cbranch_scc1 .Lml2_den2_4
.Lml2_back2_4:
	v_cvt_pk_bf16_f32 v28, v26, v26
	s_mov_b64 exec, s[18:19]
	global_store_short v58, v28, s[14:15] offset:-4096
	s_mov_b64 exec, -1
	s_waitcnt lgkmcnt(2)
	v_pk_mul_f32 v[18:19], v[44:45], v[54:55] op_sel:[0,1] op_sel_hi:[1,1]
	v_pk_mul_f32 v[20:21], v[46:47], v[54:55] op_sel:[0,1] op_sel_hi:[1,1]
	s_waitcnt lgkmcnt(1)
	v_pk_mul_f32 v[22:23], v[52:53], v[18:19] op_sel:[0,0] op_sel_hi:[1,0]
	v_pk_fma_f32 v[6:7], v[6:7], v[54:55], v[22:23] op_sel_hi:[1,0,1]
	s_waitcnt lgkmcnt(0)
	v_pk_mul_f32 v[26:27], v[6:7], v[48:49] op_sel_hi:[1,0]
	v_pk_mul_f32 v[24:25], v[52:53], v[18:19] op_sel:[0,1] op_sel_hi:[1,1]
	v_pk_fma_f32 v[8:9], v[8:9], v[54:55], v[24:25] op_sel_hi:[1,0,1]
	v_pk_fma_f32 v[26:27], v[8:9], v[48:49], v[26:27] op_sel:[0,1,0] op_sel_hi:[1,1,1]
	v_pk_mul_f32 v[22:23], v[52:53], v[20:21] op_sel:[0,0] op_sel_hi:[1,0]
	v_pk_fma_f32 v[10:11], v[10:11], v[54:55], v[22:23] op_sel_hi:[1,0,1]
	v_pk_fma_f32 v[26:27], v[10:11], v[50:51], v[26:27] op_sel:[0,0,0] op_sel_hi:[1,0,1]
	v_pk_mul_f32 v[24:25], v[52:53], v[20:21] op_sel:[0,1] op_sel_hi:[1,1]
	v_pk_fma_f32 v[12:13], v[12:13], v[54:55], v[24:25] op_sel_hi:[1,0,1]
	v_pk_fma_f32 v[26:27], v[12:13], v[50:51], v[26:27] op_sel:[0,1,0] op_sel_hi:[1,1,1]
	v_pk_fma_f32 v[14:15], v[14:15], v[54:55], v[18:19] op_sel_hi:[1,0,1]
	v_pk_fma_f32 v[16:17], v[16:17], v[54:55], v[20:21] op_sel_hi:[1,0,1]
	v_add_f32_dpp v26, v26, v26 row_ror:8 row_mask:0xf bank_mask:0x3 bound_ctrl:1
	v_add_f32_dpp v26, v27, v27 row_ror:8 row_mask:0xf bank_mask:0xc bound_ctrl:1
	ds_read_b128 v[40:43], v1 offset:47712
	ds_read_b128 v[30:33], v2 offset:44288
	v_add_f32_dpp v26, v26, v26 row_half_mirror row_mask:0xf bank_mask:0xf bound_ctrl:1
	ds_read_b64 v[38:39], v3 offset:46848
	ds_read_b128 v[34:37], v2 offset:44544
	v_add_f32_dpp v26, v26, v26 quad_perm:[1,0,3,2] row_mask:0xf bank_mask:0xf bound_ctrl:1
	s_add_u32 s14, s14, 0x1000
	s_addc_u32 s15, s15, 0
	v_add_f32_dpp v26, v26, v26 quad_perm:[2,3,0,1] row_mask:0xf bank_mask:0xf bound_ctrl:1
	s_cmp_eq_u32 s21, 5
	s_cbranch_scc1 .Lml2_den2_5
.Lml2_back2_5:
	v_cvt_pk_bf16_f32 v28, v26, v26
	s_mov_b64 exec, s[18:19]
	global_store_short v58, v28, s[14:15] offset:-4096
	s_mov_b64 exec, -1
	s_waitcnt lgkmcnt(2)
	v_pk_mul_f32 v[18:19], v[30:31], v[40:41] op_sel:[0,1] op_sel_hi:[1,1]
	v_pk_mul_f32 v[20:21], v[32:33], v[40:41] op_sel:[0,1] op_sel_hi:[1,1]
	s_waitcnt lgkmcnt(1)
	v_pk_mul_f32 v[22:23], v[38:39], v[18:19] op_sel:[0,0] op_sel_hi:[1,0]
	v_pk_fma_f32 v[6:7], v[6:7], v[40:41], v[22:23] op_sel_hi:[1,0,1]
	s_waitcnt lgkmcnt(0)
	v_pk_mul_f32 v[26:27], v[6:7], v[34:35] op_sel_hi:[1,0]
	v_pk_mul_f32 v[24:25], v[38:39], v[18:19] op_sel:[0,1] op_sel_hi:[1,1]
	v_pk_fma_f32 v[8:9], v[8:9], v[40:41], v[24:25] op_sel_hi:[1,0,1]
	v_pk_fma_f32 v[26:27], v[8:9], v[34:35], v[26:27] op_sel:[0,1,0] op_sel_hi:[1,1,1]
	v_pk_mul_f32 v[22:23], v[38:39], v[20:21] op_sel:[0,0] op_sel_hi:[1,0]
	v_pk_fma_f32 v[10:11], v[10:11], v[40:41], v[22:23] op_sel_hi:[1,0,1]
	v_pk_fma_f32 v[26:27], v[10:11], v[36:37], v[26:27] op_sel:[0,0,0] op_sel_hi:[1,0,1]
	v_pk_mul_f32 v[24:25], v[38:39], v[20:21] op_sel:[0,1] op_sel_hi:[1,1]
	v_pk_fma_f32 v[12:13], v[12:13], v[40:41], v[24:25] op_sel_hi:[1,0,1]
	v_pk_fma_f32 v[26:27], v[12:13], v[36:37], v[26:27] op_sel:[0,1,0] op_sel_hi:[1,1,1]
	v_pk_fma_f32 v[14:15], v[14:15], v[40:41], v[18:19] op_sel_hi:[1,0,1]
	v_pk_fma_f32 v[16:17], v[16:17], v[40:41], v[20:21] op_sel_hi:[1,0,1]
	v_add_f32_dpp v26, v26, v26 row_ror:8 row_mask:0xf bank_mask:0x3 bound_ctrl:1
	v_add_f32_dpp v26, v27, v27 row_ror:8 row_mask:0xf bank_mask:0xc bound_ctrl:1
	ds_read_b128 v[54:57], v1 offset:47728
	ds_read_b128 v[44:47], v2 offset:44800
	v_add_f32_dpp v26, v26, v26 row_half_mirror row_mask:0xf bank_mask:0xf bound_ctrl:1
	ds_read_b64 v[52:53], v3 offset:47104
	ds_read_b128 v[48:51], v2 offset:45056
	v_add_f32_dpp v26, v26, v26 quad_perm:[1,0,3,2] row_mask:0xf bank_mask:0xf bound_ctrl:1
	s_add_u32 s14, s14, 0x1000
	s_addc_u32 s15, s15, 0
	v_add_f32_dpp v26, v26, v26 quad_perm:[2,3,0,1] row_mask:0xf bank_mask:0xf bound_ctrl:1
	s_cmp_eq_u32 s21, 6
	s_cbranch_scc1 .Lml2_den2_6
.Lml2_back2_6:
	v_cvt_pk_bf16_f32 v28, v26, v26
	s_mov_b64 exec, s[18:19]
	global_store_short v58, v28, s[14:15] offset:-4096
	s_mov_b64 exec, -1
	s_waitcnt lgkmcnt(2)
	v_pk_mul_f32 v[18:19], v[44:45], v[54:55] op_sel:[0,1] op_sel_hi:[1,1]
	v_pk_mul_f32 v[20:21], v[46:47], v[54:55] op_sel:[0,1] op_sel_hi:[1,1]
	s_waitcnt lgkmcnt(1)
	v_pk_mul_f32 v[22:23], v[52:53], v[18:19] op_sel:[0,0] op_sel_hi:[1,0]
	v_pk_fma_f32 v[6:7], v[6:7], v[54:55], v[22:23] op_sel_hi:[1,0,1]
	s_waitcnt lgkmcnt(0)
	v_pk_mul_f32 v[26:27], v[6:7], v[48:49] op_sel_hi:[1,0]
	v_pk_mul_f32 v[24:25], v[52:53], v[18:19] op_sel:[0,1] op_sel_hi:[1,1]
	v_pk_fma_f32 v[8:9], v[8:9], v[54:55], v[24:25] op_sel_hi:[1,0,1]
	v_pk_fma_f32 v[26:27], v[8:9], v[48:49], v[26:27] op_sel:[0,1,0] op_sel_hi:[1,1,1]
	v_pk_mul_f32 v[22:23], v[52:53], v[20:21] op_sel:[0,0] op_sel_hi:[1,0]
	v_pk_fma_f32 v[10:11], v[10:11], v[54:55], v[22:23] op_sel_hi:[1,0,1]
	v_pk_fma_f32 v[26:27], v[10:11], v[50:51], v[26:27] op_sel:[0,0,0] op_sel_hi:[1,0,1]
	v_pk_mul_f32 v[24:25], v[52:53], v[20:21] op_sel:[0,1] op_sel_hi:[1,1]
	v_pk_fma_f32 v[12:13], v[12:13], v[54:55], v[24:25] op_sel_hi:[1,0,1]
	v_pk_fma_f32 v[26:27], v[12:13], v[50:51], v[26:27] op_sel:[0,1,0] op_sel_hi:[1,1,1]
	v_pk_fma_f32 v[14:15], v[14:15], v[54:55], v[18:19] op_sel_hi:[1,0,1]
	v_pk_fma_f32 v[16:17], v[16:17], v[54:55], v[20:21] op_sel_hi:[1,0,1]
	v_add_f32_dpp v26, v26, v26 row_ror:8 row_mask:0xf bank_mask:0x3 bound_ctrl:1
	v_add_f32_dpp v26, v27, v27 row_ror:8 row_mask:0xf bank_mask:0xc bound_ctrl:1
	ds_read_b128 v[40:43], v1 offset:14848
	ds_read_b128 v[30:33], v2 offset:8448
	v_add_f32_dpp v26, v26, v26 row_half_mirror row_mask:0xf bank_mask:0xf bound_ctrl:1
	ds_read_b64 v[38:39], v3 offset:12544
	ds_read_b128 v[34:37], v2 offset:8704
	v_add_f32_dpp v26, v26, v26 quad_perm:[1,0,3,2] row_mask:0xf bank_mask:0xf bound_ctrl:1
	s_add_u32 s14, s14, 0x1000
	s_addc_u32 s15, s15, 0
	v_add_f32_dpp v26, v26, v26 quad_perm:[2,3,0,1] row_mask:0xf bank_mask:0xf bound_ctrl:1
	s_cmp_eq_u32 s21, 7
	s_cbranch_scc1 .Lml2_den2_7
.Lml2_back2_7:
	v_cvt_pk_bf16_f32 v28, v26, v26
	s_mov_b64 exec, s[18:19]
	global_store_short v58, v28, s[14:15] offset:-4096
	s_mov_b64 exec, -1
	s_waitcnt vmcnt(8)
	v_lshlrev_b32_e32 v88, 16, v80
	v_lshlrev_b32_e32 v89, 16, v81
	v_and_b32_e32 v90, s17, v80
	v_and_b32_e32 v91, s17, v81
	v_lshlrev_b32_e32 v92, 16, v82
	v_and_b32_e32 v93, s17, v82
	v_lshlrev_b32_e32 v94, 16, v83
	v_and_b32_e32 v95, s17, v83
	v_lshlrev_b32_e32 v96, 16, v84
	v_and_b32_e32 v97, s17, v84
	ds_write_b128 v69, v[88:91] offset:16640
	ds_write_b64 v70, v[92:93] offset:16640
	ds_write_b64 v71, v[94:95] offset:16640
	ds_write_b64 v71, v[96:97] offset:16768
	ds_write_b32 v72, v85 offset:16640
	s_cmp_lg_u32 s36, 4
	s_cbranch_scc1 .Lml2_nsc4
	v_mov_b32_e32 v98, v87
	s_nop 1
	v_add_f32_dpp v98, v98, v98 row_shr:1 row_mask:0xf bank_mask:0xf bound_ctrl:1
	s_nop 1
	v_add_f32_dpp v98, v98, v98 row_shr:2 row_mask:0xf bank_mask:0xf bound_ctrl:1
	s_nop 1
	v_add_f32_dpp v98, v98, v98 row_shr:4 row_mask:0xf bank_mask:0xf bound_ctrl:1
	s_nop 1
	v_sub_f32_e32 v99, v86, v98
	s_nop 1
	v_max_f32_dpp v99, v99, v99 row_shr:1 row_mask:0xf bank_mask:0xf
	s_nop 1
	v_max_f32_dpp v99, v99, v99 row_shr:2 row_mask:0xf bank_mask:0xf
	s_nop 1
	v_max_f32_dpp v99, v99, v99 row_shr:4 row_mask:0xf bank_mask:0xf
	s_nop 1
	v_max_f32_e32 v99, v99, v0
	v_add_f32_e32 v103, v98, v99
	v_mov_b32_e32 v105, v0
	s_nop 1
	v_mov_b32_dpp v105, v103 row_shr:1 row_mask:0xf bank_mask:0xf
	v_sub_f32_e32 v104, v86, v103
	v_add_f32_e32 v105, v87, v105
	v_fma_f32 v104, v104, s29, v29
	v_sub_f32_e32 v105, v105, v103
	v_exp_f32_e32 v101, v104
	v_mul_f32_e32 v105, s29, v105
	v_mul_f32_e32 v104, 0xbfb8aa3b, v103
	v_exp_f32_e32 v100, v105
	v_exp_f32_e32 v102, v104
	v_readlane_b32 s4, v103, 7
	s_nop 3
	v_mov_b32_e32 v0, s4
	ds_write_b128 v73, v[100:103] offset:16640
